# attention tile row maximum: cross-row reduction with v_permlane16_swap / v_permlane32_swap instead of two ds_bpermute round trips
# speedup vs baseline: 1.0062x; 1.0062x over previous
.LBB0_206:
	v_sub_f32_e32 v108, v108, v211
	v_exp_f32_e32 v108, v108
	v_sub_f32_e32 v109, v109, v211
	v_exp_f32_e32 v109, v109
	v_sub_f32_e32 v110, v110, v211
	v_exp_f32_e32 v110, v110
	v_sub_f32_e32 v111, v111, v211
	v_exp_f32_e32 v111, v111
	v_sub_f32_e32 v104, v104, v211
	v_add_f32_e32 v129, 0, v108
	v_exp_f32_e32 v104, v104
	v_sub_f32_e32 v105, v105, v211
	v_add_f32_e32 v129, v109, v129
	v_exp_f32_e32 v105, v105
	v_sub_f32_e32 v106, v106, v211
	v_add_f32_e32 v129, v110, v129
	v_exp_f32_e32 v106, v106
	v_sub_f32_e32 v107, v107, v211
	v_add_f32_e32 v129, v111, v129
	v_exp_f32_e32 v107, v107
	v_sub_f32_e32 v100, v100, v211
	v_add_f32_e32 v129, v104, v129
	v_exp_f32_e32 v100, v100
	v_sub_f32_e32 v101, v101, v211
	v_add_f32_e32 v129, v105, v129
	v_exp_f32_e32 v101, v101
	v_sub_f32_e32 v102, v102, v211
	v_add_f32_e32 v129, v106, v129
	v_exp_f32_e32 v102, v102
	v_sub_f32_e32 v103, v103, v211
	v_add_f32_e32 v129, v107, v129
	v_exp_f32_e32 v103, v103
	v_sub_f32_e32 v96, v96, v211
	v_add_f32_e32 v129, v100, v129
	v_exp_f32_e32 v131, v96
	v_add_f32_e32 v129, v101, v129
	v_add_f32_e32 v129, v102, v129
	v_add_f32_e32 v129, v103, v129
	v_sub_f32_e32 v97, v97, v211
	v_add_f32_e32 v96, v131, v129
	v_exp_f32_e32 v129, v97
	v_sub_f32_e32 v97, v98, v211
	v_exp_f32_e32 v133, v97
	v_sub_f32_e32 v97, v99, v211
	v_exp_f32_e32 v172, v97
	v_add_f32_e32 v96, v129, v96
	v_cvt_pk_bf16_f32 v100, v100, v101
	v_cvt_pk_bf16_f32 v101, v102, v103
	v_cvt_pk_bf16_f32 v102, v131, v129
	v_add_u32_e32 v129, s90, v115
	v_add_f32_e32 v96, v133, v96
	v_add_u32_e32 v131, v129, v138
	v_add_f32_e32 v225, v172, v96
	v_cvt_pk_bf16_f32 v96, v108, v109
	v_cvt_pk_bf16_f32 v97, v110, v111
	v_cvt_pk_bf16_f32 v98, v104, v105
	v_cvt_pk_bf16_f32 v99, v106, v107
	v_cvt_pk_bf16_f32 v103, v133, v172
	ds_read_b64_tr_b16 v[106:107], v131 offset:23168
	ds_read_b64_tr_b16 v[104:105], v131 offset:18560
	ds_read_b64_tr_b16 v[108:109], v131 offset:18592
	ds_read_b64_tr_b16 v[110:111], v131 offset:23200
	ds_read_b64_tr_b16 v[172:173], v131 offset:18624
	ds_read_b64_tr_b16 v[174:175], v131 offset:23232
	ds_read_b64_tr_b16 v[226:227], v131 offset:18656
	ds_read_b64_tr_b16 v[228:229], v131 offset:23264
	s_waitcnt lgkmcnt(8)
	v_mfma_f32_16x16x32_bf16 v[76:79], v[84:87], v[96:99], v[76:79]
	v_mfma_f32_16x16x32_bf16 v[72:75], v[80:83], v[96:99], v[72:75]
	v_mfma_f32_16x16x32_bf16 v[68:71], v[88:91], v[96:99], v[68:71]
	v_mfma_f32_16x16x32_bf16 v[64:67], v[92:95], v[96:99], v[64:67]
	v_add_u32_e32 v129, v129, v196
	ds_read_b64_tr_b16 v[80:81], v129 offset:18432
	ds_read_b64_tr_b16 v[84:85], v129 offset:18464
	ds_read_b64_tr_b16 v[88:89], v129 offset:18496
	ds_read_b64_tr_b16 v[92:93], v129 offset:18528
	ds_read_b64_tr_b16 v[82:83], v131 offset:32256
	ds_read_b64_tr_b16 v[86:87], v131 offset:32288
	ds_read_b64_tr_b16 v[90:91], v131 offset:32320
	ds_read_b64_tr_b16 v[94:95], v131 offset:32352
	s_waitcnt lgkmcnt(14)
	v_mfma_f32_16x16x32_bf16 v[60:63], v[104:107], v[96:99], v[60:63]
	s_waitcnt lgkmcnt(12)
	v_mfma_f32_16x16x32_bf16 v[24:27], v[108:111], v[96:99], v[24:27]
	s_waitcnt lgkmcnt(10)
	v_mfma_f32_16x16x32_bf16 v[20:23], v[172:175], v[96:99], v[20:23]
	s_waitcnt lgkmcnt(8)
	v_mfma_f32_16x16x32_bf16 v[16:19], v[226:229], v[96:99], v[16:19]
	ds_read_b64_tr_b16 v[96:97], v129 offset:18560
	ds_read_b64_tr_b16 v[104:105], v129 offset:18592
	ds_read_b64_tr_b16 v[108:109], v129 offset:18624
	ds_read_b64_tr_b16 v[172:173], v129 offset:18656
	ds_read_b64_tr_b16 v[98:99], v131 offset:32384
	ds_read_b64_tr_b16 v[106:107], v131 offset:32416
	ds_read_b64_tr_b16 v[110:111], v131 offset:32448
	ds_read_b64_tr_b16 v[174:175], v131 offset:32480
	s_waitcnt lgkmcnt(11)
	v_mfma_f32_16x16x32_bf16 v[76:79], v[80:83], v[100:103], v[76:79]
	s_waitcnt lgkmcnt(10)
	v_mfma_f32_16x16x32_bf16 v[72:75], v[84:87], v[100:103], v[72:75]
	s_waitcnt lgkmcnt(9)
	v_mfma_f32_16x16x32_bf16 v[68:71], v[88:91], v[100:103], v[68:71]
	s_waitcnt lgkmcnt(8)
	v_mfma_f32_16x16x32_bf16 v[64:67], v[92:95], v[100:103], v[64:67]
	s_waitcnt lgkmcnt(3)
	v_mfma_f32_16x16x32_bf16 v[60:63], v[96:99], v[100:103], v[60:63]
	s_waitcnt lgkmcnt(2)
	v_mfma_f32_16x16x32_bf16 v[24:27], v[104:107], v[100:103], v[24:27]
	s_waitcnt lgkmcnt(1)
	v_mfma_f32_16x16x32_bf16 v[20:23], v[108:111], v[100:103], v[20:23]
	s_waitcnt lgkmcnt(0)
	v_mfma_f32_16x16x32_bf16 v[16:19], v[172:175], v[100:103], v[16:19]
	v_add_f32_e32 v205, v205, v225

.LBB0_370:
	s_mov_b32 s12, 0xf149f2ca
	v_max3_f32 v129, v108, s12, v109
	v_max3_f32 v129, v129, v110, v111
	v_max3_f32 v129, v129, v104, v105
	v_max3_f32 v129, v129, v106, v107
	v_max3_f32 v129, v129, v100, v101
	v_max3_f32 v129, v129, v102, v103
	v_max3_f32 v129, v129, v96, v97
	v_max3_f32 v129, v129, v98, v99
	s_mov_b32 s12, 0x41000000
	v_mov_b32_e32 v131, v129
	s_nop 1
	v_permlane16_swap_b32_e32 v131, v129
	s_nop 1
	v_max_f32_e32 v129, v129, v131
	v_mov_b32_e32 v131, v129
	s_nop 1
	v_permlane32_swap_b32_e32 v131, v129
	s_nop 1
	v_max_f32_e32 v129, v129, v131
	v_sub_f32_e32 v131, v129, v211
	v_cmp_lt_f32_e32 vcc, s12, v131
	s_cbranch_vccz .LBB0_206
	v_max_f32_e32 v129, v129, v129
	v_max_f32_e32 v131, v211, v211
	v_max_f32_e32 v129, v131, v129
	v_sub_f32_e32 v131, v211, v129
	v_exp_f32_e32 v172, v131
	v_mov_b32_e32 v211, v129
	v_pk_mul_f32 v[78:79], v[78:79], v[172:173] op_sel_hi:[1,0]
	v_pk_mul_f32 v[76:77], v[76:77], v[172:173] op_sel_hi:[1,0]
	v_pk_mul_f32 v[74:75], v[74:75], v[172:173] op_sel_hi:[1,0]
	v_pk_mul_f32 v[72:73], v[72:73], v[172:173] op_sel_hi:[1,0]
	v_pk_mul_f32 v[70:71], v[70:71], v[172:173] op_sel_hi:[1,0]
	v_pk_mul_f32 v[68:69], v[68:69], v[172:173] op_sel_hi:[1,0]
	v_pk_mul_f32 v[66:67], v[66:67], v[172:173] op_sel_hi:[1,0]
	v_pk_mul_f32 v[64:65], v[64:65], v[172:173] op_sel_hi:[1,0]
	v_pk_mul_f32 v[62:63], v[62:63], v[172:173] op_sel_hi:[1,0]
	v_pk_mul_f32 v[60:61], v[60:61], v[172:173] op_sel_hi:[1,0]
	v_pk_mul_f32 v[26:27], v[26:27], v[172:173] op_sel_hi:[1,0]
	v_pk_mul_f32 v[24:25], v[24:25], v[172:173] op_sel_hi:[1,0]
	v_pk_mul_f32 v[22:23], v[22:23], v[172:173] op_sel_hi:[1,0]
	v_pk_mul_f32 v[20:21], v[20:21], v[172:173] op_sel_hi:[1,0]
	v_pk_mul_f32 v[18:19], v[18:19], v[172:173] op_sel_hi:[1,0]
	v_pk_mul_f32 v[16:17], v[16:17], v[172:173] op_sel_hi:[1,0]
	v_mul_f32_e32 v205, v205, v172
	s_branch .LBB0_206
